# next layer's ffn1 + w_in weight conversion moved from the merge GEMM tail (no longer idle) to the ffn2 gate/up GEMM's idle last round
# speedup vs baseline: 1.0205x; 1.0022x over previous
.LBB0_1225:
	s_cmp_eq_u32 s87, 6
	v_readlane_b32 s4, v254, 49
	s_cselect_b64 s[0:1], -1, 0
	v_readlane_b32 s5, v254, 50
	s_and_b64 s[0:1], s[4:5], s[0:1]
	v_readlane_b32 s4, v254, 17
	v_readlane_b32 s5, v254, 18
	v_cndmask_b32_e64 v0, 0, 1, s[0:1]
	s_mov_b64 s[6:7], -1
	s_and_b64 vcc, exec, s[4:5]
	v_cmp_ne_u32_e64 s[38:39], 1, v0
	s_cbranch_vccz .LBB0_1792
	s_and_b64 vcc, exec, s[38:39]
	s_cbranch_vccnz .LBB0_1478
	v_mov_b32_e32 v0, s64
	v_mov_b32_e32 v2, s65
	s_waitcnt vmcnt(0)
	s_barrier
	s_nop 0
	v_readfirstlane_b32 s0, v0
	v_readfirstlane_b32 s1, v2
	v_mov_b32_e32 v0, s88
	v_mov_b32_e32 v2, s0
	v_mov_b32_e32 v3, s1
	flat_load_dwordx2 v[2:3], v[2:3] offset:248
	s_waitcnt vmcnt(0) lgkmcnt(0)
	s_nop 0
	v_readfirstlane_b32 s1, v0
	v_readfirstlane_b32 s0, v2
	s_cmpk_gt_u32 s1, 0x3cf
	v_readfirstlane_b32 s4, v3
	s_cbranch_scc1 .LBB0_1478
	s_add_u32 s5, s0, 0x1080000
	s_addc_u32 s20, s4, 0
	s_add_u32 s21, s0, 0xb00000
	v_readlane_b32 s6, v253, 0
	s_addc_u32 s33, s4, 0
	s_lshl_b32 s34, s1, 8
	s_lshl_b32 s35, s6, 8
	s_lshl_b32 s46, s1, 4
	s_lshl_b32 s47, s6, 4
	v_readlane_b32 s7, v253, 1
	s_branch .LBB0_1231

.LBB0_1792:
	s_and_b64 vcc, exec, s[6:7]
	s_cbranch_vccz .LBB0_2359
	s_and_b64 vcc, exec, s[38:39]
	s_cbranch_vccnz .LBB0_2046
	v_mov_b32_e32 v0, s64
	v_mov_b32_e32 v2, s65
	s_nop 0
	v_readfirstlane_b32 s0, v0
	v_readfirstlane_b32 s1, v2
	v_mov_b32_e32 v0, s88
	v_mov_b32_e32 v2, s0
	v_mov_b32_e32 v3, s1
	flat_load_dwordx2 v[2:3], v[2:3] offset:248
	s_waitcnt vmcnt(0) lgkmcnt(0)
	s_nop 0
	v_readfirstlane_b32 s4, v0
	v_readfirstlane_b32 s0, v2
	s_cmp_lt_i32 s4, 48
	v_readfirstlane_b32 s1, v3
	s_cbranch_scc1 .LBB0_2046
	s_sub_i32 s4, s4, 48
	s_cmpk_gt_u32 s4, 0x3cf
	s_cbranch_scc1 .LBB0_2046
	s_add_u32 s5, s0, 0x1080000
	s_addc_u32 s20, s1, 0
	s_add_u32 s21, s0, 0xb00000
	v_readlane_b32 s6, v254, 21
	s_addc_u32 s33, s1, 0
	s_lshl_b32 s34, s4, 8
	s_lshl_b32 s35, s6, 8
	s_lshl_b32 s44, s4, 4
	s_lshl_b32 s45, s6, 4
	s_branch .LBB0_1799

.LBB0_1798:
	v_readlane_b32 s6, v254, 21
	s_add_i32 s4, s4, s6
	s_add_i32 s34, s34, s35
	s_add_i32 s44, s44, s45
	s_cmpk_lt_i32 s4, 0x3d0
	s_cbranch_scc0 .LBB0_2046
